# mixer-C prologue: compressed K/V staging loads issued together (8 loads, counted waits) instead of one per wait
# speedup vs baseline: 1.0150x; 1.0097x over previous
.LBB0_425:
	s_and_b64 vcc, exec, s[0:1]
	s_cbranch_vccz .LBB0_476
	v_readlane_b32 s0, v254, 50
	s_lshl_b32 s0, s0, 2
	s_and_b32 s1, s10, 3
	s_or_b32 s0, s0, s1
	s_ashr_i32 s14, s10, 2
	s_waitcnt vmcnt(0)
	v_and_b32_e32 v150, 31, v198
	s_lshl_b32 s12, s0, 5
	v_or_b32_e32 v206, s12, v150
	s_ashr_i32 s15, s14, 31
	v_writelane_b32 v254, s0, 52
	s_lshl_b64 s[0:1], s[14:15], 11
	v_ashrrev_i32_e32 v207, 31, v206
	v_lshl_add_u64 v[200:201], s[0:1], 0, v[206:207]
	v_readlane_b32 s0, v254, 3
	v_readlane_b32 s1, v254, 4
	s_movk_i32 s8, 0x1d00
	v_and_b32_e32 v204, 0xffffffc0, v198
	v_mov_b64_e32 v[0:1], s[0:1]
	v_mad_u64_u32 v[202:203], s[0:1], v200, s8, v[0:1]
	v_bfe_u32 v64, v198, 5, 1
	v_mad_i32_i24 v203, v201, s8, v203
	v_ashrrev_i32_e32 v205, 31, v204
	v_lshl_add_u64 v[0:1], v[204:205], 1, v[202:203]
	v_lshlrev_b32_e32 v192, 4, v64
	v_lshl_add_u64 v[0:1], v[0:1], 0, v[192:193]
	v_ashrrev_i32_e32 v66, 6, v198
	global_load_dwordx4 v[160:163], v[0:1], off offset:3328
	global_load_dwordx4 v[164:167], v[0:1], off offset:3360
	global_load_dwordx4 v[168:171], v[0:1], off offset:3392
	global_load_dwordx4 v[172:175], v[0:1], off offset:3424
	v_lshl_add_u32 v0, v66, 1, v66
	v_ashrrev_i32_e32 v1, 31, v0
	v_lshl_add_u64 v[0:1], v[0:1], 1, v[202:203]
	s_mov_b64 s[0:1], 0x1c40
	v_lshl_add_u64 v[2:3], v[0:1], 0, s[0:1]
	s_movk_i32 s0, 0x1000
	v_add_co_u32_e32 v0, vcc, s0, v0
	s_mov_b32 s0, s14
	v_writelane_b32 v254, s0, 53
	v_addc_co_u32_e32 v1, vcc, 0, v1, vcc
	s_nop 0
	v_writelane_b32 v254, s1, 54
	s_lshl_b64 s[0:1], s[14:15], 14
	v_readlane_b32 s8, v254, 5
	global_load_dword v199, v[0:1], off offset:3136
	global_load_ushort v197, v[2:3], off offset:4
	s_add_u32 s8, s8, s0
	v_readlane_b32 s9, v254, 6
	v_lshlrev_b32_e32 v0, 4, v198
	v_ashrrev_i32_e32 v65, 3, v198
	s_addc_u32 s9, s9, s1
	v_and_b32_e32 v192, 0x70, v0
	v_lshlrev_b32_e32 v0, 6, v65
	v_lshl_add_u64 v[4:5], s[8:9], 0, v[192:193]
	v_ashrrev_i32_e32 v1, 31, v0
	v_lshl_add_u64 v[0:1], v[0:1], 1, v[4:5]
	s_waitcnt lgkmcnt(0)
	s_barrier
	global_load_dwordx4 v[112:115], v[0:1], off
	s_movk_i32 s10, 0x90
	v_add_u32_e32 v151, 0x100, v198
	v_add_u32_e32 v10, 0x200, v198
	v_add_u32_e32 v11, 0x300, v198
	v_cmp_gt_i32_e32 vcc, 32, v198
	v_ashrrev_i32_e32 v144, 3, v151
	v_lshlrev_b32_e32 v0, 6, v144
	v_ashrrev_i32_e32 v1, 31, v0
	v_lshl_add_u64 v[0:1], v[0:1], 1, v[4:5]
	global_load_dwordx4 v[116:119], v[0:1], off
	v_ashrrev_i32_e32 v145, 3, v10
	v_lshlrev_b32_e32 v0, 6, v145
	v_ashrrev_i32_e32 v1, 31, v0
	v_lshl_add_u64 v[0:1], v[0:1], 1, v[4:5]
	global_load_dwordx4 v[120:123], v[0:1], off
	v_ashrrev_i32_e32 v146, 3, v11
	v_lshlrev_b32_e32 v0, 6, v146
	v_ashrrev_i32_e32 v1, 31, v0
	v_lshl_add_u64 v[0:1], v[0:1], 1, v[4:5]
	global_load_dwordx4 v[124:127], v[0:1], off
	v_mad_u32_u24 v147, v65, s10, v192
	v_mad_u32_u24 v148, v144, s10, v192
	v_mad_u32_u24 v149, v145, s10, v192
	v_mad_u32_u24 v144, v146, s10, v192
	v_readlane_b32 s8, v254, 7
	s_add_u32 s0, s8, s0
	v_readlane_b32 s8, v254, 8
	s_addc_u32 s1, s8, s1
	s_movk_i32 s8, 0x108
	s_movk_i32 s10, 0x108
	v_and_b32_e32 v0, 0x7f, v198
	v_lshlrev_b32_e32 v192, 7, v0
	v_lshl_add_u64 v[2:3], s[0:1], 0, v[192:193]
	v_lshlrev_b32_e32 v0, 1, v0
	v_ashrrev_i32_e32 v1, 4, v198
	v_and_b32_e32 v4, -8, v1
	v_ashrrev_i32_e32 v5, 31, v4
	v_lshl_add_u64 v[6:7], v[4:5], 1, v[2:3]
	global_load_dwordx4 v[128:131], v[6:7], off
	v_mad_u32_u24 v145, v4, s8, v0
	v_ashrrev_i32_e32 v1, 4, v151
	v_and_b32_e32 v4, -8, v1
	v_ashrrev_i32_e32 v5, 31, v4
	v_lshl_add_u64 v[6:7], v[4:5], 1, v[2:3]
	global_load_dwordx4 v[132:135], v[6:7], off
	v_mad_u32_u24 v146, v4, s8, v0
	v_ashrrev_i32_e32 v1, 4, v10
	v_and_b32_e32 v4, -8, v1
	v_ashrrev_i32_e32 v5, 31, v4
	v_lshl_add_u64 v[6:7], v[4:5], 1, v[2:3]
	global_load_dwordx4 v[136:139], v[6:7], off
	v_mad_u32_u24 v8, v4, s8, v0
	v_ashrrev_i32_e32 v1, 4, v11
	v_and_b32_e32 v4, -8, v1
	v_ashrrev_i32_e32 v5, 31, v4
	v_lshl_add_u64 v[6:7], v[4:5], 1, v[2:3]
	global_load_dwordx4 v[140:143], v[6:7], off
	v_mad_u32_u24 v9, v4, s8, v0
	s_waitcnt vmcnt(7)
	ds_write_b128 v147, v[112:115]
	s_waitcnt vmcnt(6)
	ds_write_b128 v148, v[116:119]
	s_waitcnt vmcnt(5)
	ds_write_b128 v149, v[120:123]
	s_waitcnt vmcnt(4)
	ds_write_b128 v144, v[124:127]
	s_waitcnt vmcnt(3)
	ds_write_b16 v145, v128 offset:18432
	ds_write_b16_d16_hi v145, v128 offset:18696
	ds_write_b16 v145, v129 offset:18960
	ds_write_b16_d16_hi v145, v129 offset:19224
	ds_write_b16 v145, v130 offset:19488
	ds_write_b16_d16_hi v145, v130 offset:19752
	ds_write_b16 v145, v131 offset:20016
	ds_write_b16_d16_hi v145, v131 offset:20280
	s_waitcnt vmcnt(2)
	ds_write_b16 v146, v132 offset:18432
	ds_write_b16_d16_hi v146, v132 offset:18696
	ds_write_b16 v146, v133 offset:18960
	ds_write_b16_d16_hi v146, v133 offset:19224
	ds_write_b16 v146, v134 offset:19488
	ds_write_b16_d16_hi v146, v134 offset:19752
	ds_write_b16 v146, v135 offset:20016
	ds_write_b16_d16_hi v146, v135 offset:20280
	s_waitcnt vmcnt(1)
	ds_write_b16 v8, v136 offset:18432
	ds_write_b16_d16_hi v8, v136 offset:18696
	ds_write_b16 v8, v137 offset:18960
	ds_write_b16_d16_hi v8, v137 offset:19224
	ds_write_b16 v8, v138 offset:19488
	ds_write_b16_d16_hi v8, v138 offset:19752
	ds_write_b16 v8, v139 offset:20016
	ds_write_b16_d16_hi v8, v139 offset:20280
	s_waitcnt vmcnt(0)
	ds_write_b16 v9, v140 offset:18432
	ds_write_b16_d16_hi v9, v140 offset:18696
	ds_write_b16 v9, v141 offset:18960
	ds_write_b16_d16_hi v9, v141 offset:19224
	ds_write_b16 v9, v142 offset:19488
	ds_write_b16_d16_hi v9, v142 offset:19752
	ds_write_b16 v9, v143 offset:20016
	ds_write_b16_d16_hi v9, v143 offset:20280
	s_and_saveexec_b64 s[0:1], vcc
	v_mov_b32_e32 v0, 0x11400
	v_lshl_add_u32 v0, v198, 2, v0
	ds_write_b32 v0, v193
	s_or_b64 exec, exec, s[0:1]
	v_cmp_eq_u32_e32 vcc, 32, v198
	s_and_saveexec_b64 s[0:1], vcc
	v_mov_b32_e32 v0, 0x11480
	ds_write_b32 v0, v193
	s_or_b64 exec, exec, s[0:1]
	v_mul_u32_u24_e32 v208, 0x90, v150
	v_lshl_add_u32 v67, v64, 4, v208
	s_waitcnt lgkmcnt(0)
	s_barrier
	ds_read_b128 v[0:3], v67
	ds_read_b128 v[4:7], v67 offset:32
	s_waitcnt lgkmcnt(1)
	v_mfma_f32_32x32x16_bf16 v[48:63], v[0:3], v[160:163], 0
	ds_read_b128 v[0:3], v67 offset:64
	ds_read_b128 v[68:71], v67 offset:13856
	s_mov_b32 s8, 0x3e000000
	s_mov_b32 s0, 0xff61b1e6
	v_lshlrev_b32_e32 v235, 3, v64
	s_waitcnt lgkmcnt(2)
	v_mfma_f32_32x32x16_bf16 v[48:63], v[4:7], v[164:167], v[48:63]
	s_waitcnt lgkmcnt(1)
	v_mfma_f32_32x32x16_bf16 v[48:63], v[0:3], v[168:171], v[48:63]
	ds_read_b128 v[0:3], v67 offset:96
	s_waitcnt lgkmcnt(0)
	v_mfma_f32_32x32x16_bf16 v[48:63], v[0:3], v[172:175], v[48:63]
	ds_read_b128 v[0:3], v67 offset:4608
	s_waitcnt lgkmcnt(0)
	v_mfma_f32_32x32x16_bf16 v[32:47], v[0:3], v[160:163], 0
	ds_read_b128 v[0:3], v67 offset:4640
	s_nop 7
	v_mul_f32_e32 v50, 0x3e000000, v50
	v_mul_f32_e32 v51, 0x3e000000, v51
	v_mul_f32_e32 v54, 0x3e000000, v54
	v_mul_f32_e32 v55, 0x3e000000, v55
	v_mul_f32_e32 v58, 0x3e000000, v58
	v_mul_f32_e32 v59, 0x3e000000, v59
	s_waitcnt lgkmcnt(0)
	v_mfma_f32_32x32x16_bf16 v[32:47], v[0:3], v[164:167], v[32:47]
	ds_read_b128 v[0:3], v67 offset:4672
	v_mul_f32_e32 v62, 0x3e000000, v62
	v_mul_f32_e32 v63, 0x3e000000, v63
	s_waitcnt lgkmcnt(0)
	v_mfma_f32_32x32x16_bf16 v[32:47], v[0:3], v[168:171], v[32:47]
	ds_read_b128 v[0:3], v67 offset:4704
	s_waitcnt lgkmcnt(0)
	v_mfma_f32_32x32x16_bf16 v[32:47], v[0:3], v[172:175], v[32:47]
	ds_read_b128 v[0:3], v67 offset:9216
	s_waitcnt lgkmcnt(0)
	v_mfma_f32_32x32x16_bf16 v[16:31], v[0:3], v[160:163], 0
	ds_read_b128 v[0:3], v67 offset:9248
	s_nop 7
	v_mul_f32_e32 v34, 0x3e000000, v34
	v_mul_f32_e32 v35, 0x3e000000, v35
	v_mul_f32_e32 v38, 0x3e000000, v38
	v_mul_f32_e32 v39, 0x3e000000, v39
	v_mul_f32_e32 v42, 0x3e000000, v42
	v_mul_f32_e32 v43, 0x3e000000, v43
	s_waitcnt lgkmcnt(0)
	v_mfma_f32_32x32x16_bf16 v[16:31], v[0:3], v[164:167], v[16:31]
	ds_read_b128 v[0:3], v67 offset:9280
	v_mul_f32_e32 v46, 0x3e000000, v46
	v_mul_f32_e32 v47, 0x3e000000, v47
	s_waitcnt lgkmcnt(0)
	v_mfma_f32_32x32x16_bf16 v[16:31], v[0:3], v[168:171], v[16:31]
	ds_read_b128 v[0:3], v67 offset:9312
	s_waitcnt lgkmcnt(0)
	v_mfma_f32_32x32x16_bf16 v[16:31], v[0:3], v[172:175], v[16:31]
	ds_read_b128 v[0:3], v67 offset:13824
	s_waitcnt lgkmcnt(0)
	v_mfma_f32_32x32x16_bf16 v[0:15], v[0:3], v[160:163], 0
	s_nop 8
	v_mul_f32_e32 v18, 0x3e000000, v18
	v_mul_f32_e32 v22, 0x3e000000, v22
	v_mul_f32_e32 v23, 0x3e000000, v23
	v_mul_f32_e32 v26, 0x3e000000, v26
	v_mul_f32_e32 v27, 0x3e000000, v27
	v_mul_f32_e32 v30, 0x3e000000, v30
	v_mul_f32_e32 v31, 0x3e000000, v31
	v_mfma_f32_32x32x16_bf16 v[0:15], v[68:71], v[164:167], v[0:15]
	ds_read_b128 v[68:71], v67 offset:13888
	s_waitcnt lgkmcnt(0)
	v_mfma_f32_32x32x16_bf16 v[0:15], v[68:71], v[168:171], v[0:15]
	ds_read_b128 v[68:71], v67 offset:13920
	v_lshlrev_b32_e32 v67, 6, v64
	v_or_b32_e32 v72, 0x600, v67
	s_waitcnt lgkmcnt(0)
	v_mfma_f32_32x32x16_bf16 v[0:15], v[68:71], v[172:175], v[0:15]
	v_mul_f32_e32 v69, 0x3e000000, v19
	v_or_b32_e32 v19, 0x3bf, v67
	v_or_b32_e32 v68, 0x200, v67
	v_or_b32_e32 v71, 0x400, v67
	s_nop 7
	v_mul_f32_e32 v70, 0x3e000000, v2
	v_mbcnt_lo_u32_b32 v2, -1, 0
	v_mbcnt_hi_u32_b32 v2, -1, v2
	v_mul_f32_e32 v74, 0x3e000000, v6
	v_and_b32_e32 v6, 64, v2
	v_mul_f32_e32 v73, 0x3e000000, v3
	v_xor_b32_e32 v3, 32, v2
	v_add_u32_e32 v6, 64, v6
	v_mul_f32_e32 v77, 0x3e000000, v11
	v_cmp_lt_i32_e32 vcc, v3, v6
	v_or_b32_e32 v11, 63, v67
	v_mul_f32_e32 v76, 0x3e000000, v10
	v_cndmask_b32_e32 v2, v2, v3, vcc
	v_cmp_le_i32_e32 vcc, v11, v206
	v_add_u32_e32 v11, 0x4f, v67
	v_mul_f32_e32 v78, 0x3e000000, v14
	v_cndmask_b32_e32 v50, v226, v50, vcc
	v_cmp_le_i32_e32 vcc, v11, v206
	v_or_b32_e32 v11, 0xbf, v67
	v_or_b32_e32 v10, 0x100, v67
	v_cndmask_b32_e32 v51, v226, v51, vcc
	v_cmp_le_i32_e32 vcc, v11, v206
	v_add_u32_e32 v11, 0xcf, v67
	v_or_b32_e32 v14, 0x12f, v67
	v_cndmask_b32_e32 v54, v226, v54, vcc
	v_cmp_le_i32_e32 vcc, v11, v206
	v_mul_f32_e32 v79, 0x3e000000, v15
	v_or_b32_e32 v15, 31, v10
	v_cndmask_b32_e32 v80, v226, v55, vcc
	v_pk_mul_f32 v[10:11], v[56:57], s[8:9] op_sel_hi:[1,0]
	v_cmp_le_i32_e32 vcc, v14, v206
	v_or_b32_e32 v14, 0x2bf, v67
	v_mul_f32_e32 v75, 0x3e000000, v7
	v_cndmask_b32_e32 v57, v226, v11, vcc
	v_cmp_le_i32_e32 vcc, v15, v206
	v_pk_mul_f32 v[6:7], v[48:49], s[8:9] op_sel_hi:[1,0]
	v_pk_mul_f32 v[48:49], v[60:61], s[8:9] op_sel_hi:[1,0]
	v_cndmask_b32_e32 v81, v226, v10, vcc
	v_or_b32_e32 v10, 0x13f, v67
	v_cmp_le_i32_e32 vcc, v10, v206
	v_add_u32_e32 v10, 0x14f, v67
	v_lshlrev_b32_e32 v236, 2, v2
	v_cndmask_b32_e32 v82, v226, v58, vcc
	v_cmp_le_i32_e32 vcc, v10, v206
	v_or_b32_e32 v10, 0x1bf, v67
	v_pk_mul_f32 v[2:3], v[52:53], s[8:9] op_sel_hi:[1,0]
	v_cndmask_b32_e32 v83, v226, v59, vcc
	v_cmp_le_i32_e32 vcc, v10, v206
	v_add_u32_e32 v10, 0x1cf, v67
	v_pk_mul_f32 v[0:1], v[0:1], s[8:9] op_sel_hi:[1,0]
	v_cndmask_b32_e32 v62, v226, v62, vcc
	v_cmp_le_i32_e32 vcc, v10, v206
	v_or_b32_e32 v10, 0x23f, v67
	s_nop 0
	v_cndmask_b32_e32 v84, v226, v63, vcc
	v_cmp_le_i32_e32 vcc, v10, v206
	v_add_u32_e32 v10, 0x24f, v67
	s_nop 0
	v_cndmask_b32_e32 v11, v226, v34, vcc
	v_cmp_le_i32_e32 vcc, v10, v206
	v_or_b32_e32 v34, 0x4bf, v67
	s_nop 0
	v_cndmask_b32_e32 v10, v226, v35, vcc
	v_cmp_le_i32_e32 vcc, v14, v206
	v_add_u32_e32 v14, 0x2cf, v67
	s_nop 0
	v_cndmask_b32_e32 v55, v226, v38, vcc
	v_cmp_le_i32_e32 vcc, v14, v206
	v_or_b32_e32 v14, 0x33f, v67
	s_nop 0
	v_cndmask_b32_e32 v58, v226, v39, vcc
	v_cmp_le_i32_e32 vcc, v14, v206
	v_add_u32_e32 v14, 0x34f, v67
	s_nop 0
	v_cndmask_b32_e32 v15, v226, v42, vcc
	v_cmp_le_i32_e32 vcc, v14, v206
	s_nop 1
	v_cndmask_b32_e32 v14, v226, v43, vcc
	v_cmp_le_i32_e32 vcc, v19, v206
	v_add_u32_e32 v19, 0x3cf, v67
	s_nop 0
	v_cndmask_b32_e32 v61, v226, v46, vcc
	v_cmp_le_i32_e32 vcc, v19, v206
	v_or_b32_e32 v19, 0x43f, v67
	v_or_b32_e32 v46, 0x9f, v67
	v_cndmask_b32_e32 v59, v226, v47, vcc
	v_cmp_le_i32_e32 vcc, v19, v206
	s_nop 1
	v_cndmask_b32_e32 v19, v226, v18, vcc
	v_add_u32_e32 v18, 0x44f, v67
	v_cmp_le_i32_e32 vcc, v18, v206
	s_nop 1
	v_cndmask_b32_e32 v18, v226, v69, vcc
	v_cmp_le_i32_e32 vcc, v34, v206
	v_or_b32_e32 v34, 0xaf, v67
	s_nop 0
	v_cndmask_b32_e32 v53, v226, v22, vcc
	v_add_u32_e32 v22, 0x4cf, v67
	v_cmp_le_i32_e32 vcc, v22, v206
	v_or_b32_e32 v22, 0x53f, v67
	s_nop 0
	v_cndmask_b32_e32 v52, v226, v23, vcc
	v_cmp_le_i32_e32 vcc, v22, v206
	v_add_u32_e32 v22, 0x54f, v67
	s_nop 0
	v_cndmask_b32_e32 v23, v226, v26, vcc
	v_cmp_le_i32_e32 vcc, v22, v206
	v_or_b32_e32 v26, 0x5bf, v67
	s_nop 0
	v_cndmask_b32_e32 v22, v226, v27, vcc
	v_cmp_le_i32_e32 vcc, v26, v206
	v_add_u32_e32 v26, 0x5cf, v67
	s_nop 0
	v_cndmask_b32_e32 v47, v226, v30, vcc
	v_cmp_le_i32_e32 vcc, v26, v206
	v_or_b32_e32 v26, 0x63f, v67
	s_nop 0
	v_cndmask_b32_e32 v43, v226, v31, vcc
	v_cmp_le_i32_e32 vcc, v26, v206
	v_add_u32_e32 v26, 0x64f, v67
	s_nop 0
	v_cndmask_b32_e32 v42, v226, v70, vcc
	v_cmp_le_i32_e32 vcc, v26, v206
	v_or_b32_e32 v26, 0x6bf, v67
	s_nop 0
	v_cndmask_b32_e32 v39, v226, v73, vcc
	v_cmp_le_i32_e32 vcc, v26, v206
	v_add_u32_e32 v26, 0x6cf, v67
	s_nop 0
	v_cndmask_b32_e32 v38, v226, v74, vcc
	v_cmp_le_i32_e32 vcc, v26, v206
	v_or_b32_e32 v26, 0x73f, v67
	s_nop 0
	v_cndmask_b32_e32 v35, v226, v75, vcc
	v_cmp_le_i32_e32 vcc, v26, v206
	v_add_u32_e32 v26, 0x74f, v67
	s_nop 0
	v_cndmask_b32_e32 v31, v226, v76, vcc
	v_cmp_le_i32_e32 vcc, v26, v206
	v_or_b32_e32 v26, 0x7bf, v67
	s_nop 0
	v_cndmask_b32_e32 v30, v226, v77, vcc
	v_cmp_le_i32_e32 vcc, v26, v206
	v_add_u32_e32 v26, 0x7cf, v67
	s_nop 0
	v_cndmask_b32_e32 v27, v226, v78, vcc
	v_cmp_le_i32_e32 vcc, v26, v206
	s_nop 1
	v_cndmask_b32_e32 v26, v226, v79, vcc
	v_cmp_le_i32_e32 vcc, v34, v206
	v_or_b32_e32 v34, 0x19f, v67
	s_nop 0
	v_cndmask_b32_e32 v73, v226, v3, vcc
	v_cmp_le_i32_e32 vcc, v46, v206
	v_or_b32_e32 v3, 31, v67
	s_nop 0
	v_cndmask_b32_e32 v46, v226, v2, vcc
	v_or_b32_e32 v2, 47, v67
	v_cmp_le_i32_e32 vcc, v2, v206
	s_nop 1
	v_cndmask_b32_e32 v7, v226, v7, vcc
	v_cmp_le_i32_e32 vcc, v3, v206
	v_or_b32_e32 v3, 0x1af, v67
	s_nop 0
	v_cndmask_b32_e32 v6, v226, v6, vcc
	v_max3_f32 v2, v6, s0, v7
	v_max3_f32 v2, v2, v50, v51
	v_max3_f32 v2, v2, v46, v73
	v_max3_f32 v2, v2, v54, v80
	v_cmp_le_i32_e32 vcc, v3, v206
	v_max3_f32 v2, v2, v81, v57
	v_max3_f32 v2, v2, v82, v83
	v_cndmask_b32_e32 v74, v226, v49, vcc
	v_cmp_le_i32_e32 vcc, v34, v206
	s_nop 1
	v_cndmask_b32_e32 v75, v226, v48, vcc
	v_max3_f32 v2, v2, v75, v74
	v_max3_f32 v34, v2, v62, v84
	v_pk_mul_f32 v[2:3], v[36:37], s[8:9] op_sel_hi:[1,0]
	v_or_b32_e32 v36, 0x2af, v67
	v_or_b32_e32 v37, 0x29f, v67
	v_cmp_le_i32_e32 vcc, v36, v206
	s_nop 1
	v_cndmask_b32_e32 v76, v226, v3, vcc
	v_cmp_le_i32_e32 vcc, v37, v206
	s_nop 1
	v_cndmask_b32_e32 v77, v226, v2, vcc
	v_pk_mul_f32 v[2:3], v[32:33], s[8:9] op_sel_hi:[1,0]
	v_or_b32_e32 v32, 0x22f, v67
	v_or_b32_e32 v33, 31, v68
	v_cmp_le_i32_e32 vcc, v32, v206
	s_nop 1
	v_cndmask_b32_e32 v78, v226, v3, vcc
	v_cmp_le_i32_e32 vcc, v33, v206
	v_or_b32_e32 v33, 0x3af, v67
	s_nop 0
	v_cndmask_b32_e32 v79, v226, v2, vcc
	v_max3_f32 v2, v34, v79, v78
	v_max3_f32 v2, v2, v11, v10
	v_max3_f32 v2, v2, v77, v76
	v_max3_f32 v32, v2, v55, v58
	v_pk_mul_f32 v[2:3], v[44:45], s[8:9] op_sel_hi:[1,0]
	v_or_b32_e32 v34, 0x39f, v67
	v_cmp_le_i32_e32 vcc, v33, v206
	v_or_b32_e32 v33, 0x32f, v67
	s_nop 0
	v_cndmask_b32_e32 v69, v226, v3, vcc
	v_cmp_le_i32_e32 vcc, v34, v206
	v_or_b32_e32 v34, 0x31f, v67
	s_nop 0
	v_cndmask_b32_e32 v70, v226, v2, vcc
	v_pk_mul_f32 v[2:3], v[40:41], s[8:9] op_sel_hi:[1,0]
	v_cmp_le_i32_e32 vcc, v33, v206
	v_or_b32_e32 v33, 0x49f, v67
	s_nop 0
	v_cndmask_b32_e32 v85, v226, v3, vcc
	v_cmp_le_i32_e32 vcc, v34, v206
	s_nop 1
	v_cndmask_b32_e32 v86, v226, v2, vcc
	v_max3_f32 v2, v32, v86, v85
	v_max3_f32 v2, v2, v15, v14
	v_max3_f32 v2, v2, v70, v69
	v_max3_f32 v32, v2, v61, v59
	v_pk_mul_f32 v[2:3], v[20:21], s[8:9] op_sel_hi:[1,0]
	v_or_b32_e32 v20, 0x4af, v67
	v_cmp_le_i32_e32 vcc, v20, v206
	v_or_b32_e32 v20, 0x5af, v67
	s_nop 0
	v_cndmask_b32_e32 v21, v226, v3, vcc
	v_cmp_le_i32_e32 vcc, v33, v206
	s_nop 1
	v_cndmask_b32_e32 v63, v226, v2, vcc
	v_pk_mul_f32 v[2:3], v[16:17], s[8:9] op_sel_hi:[1,0]
	v_or_b32_e32 v16, 0x42f, v67
	v_or_b32_e32 v17, 31, v71
	v_cmp_le_i32_e32 vcc, v16, v206
	s_nop 1
	v_cndmask_b32_e32 v16, v226, v3, vcc
	v_cmp_le_i32_e32 vcc, v17, v206
	s_nop 1
	v_cndmask_b32_e32 v68, v226, v2, vcc
	v_max3_f32 v2, v32, v68, v16
	v_max3_f32 v2, v2, v19, v18
	v_max3_f32 v2, v2, v63, v21
	v_max3_f32 v17, v2, v53, v52
	v_pk_mul_f32 v[2:3], v[28:29], s[8:9] op_sel_hi:[1,0]
	v_or_b32_e32 v28, 0x59f, v67
	v_cmp_le_i32_e32 vcc, v20, v206
	v_or_b32_e32 v20, 0x52f, v67
	s_nop 0
	v_cndmask_b32_e32 v29, v226, v3, vcc
	v_cmp_le_i32_e32 vcc, v28, v206
	s_nop 1
	v_cndmask_b32_e32 v56, v226, v2, vcc
	v_pk_mul_f32 v[2:3], v[24:25], s[8:9] op_sel_hi:[1,0]
	v_or_b32_e32 v24, 0x51f, v67
	v_cmp_le_i32_e32 vcc, v20, v206
	s_nop 1
	v_cndmask_b32_e32 v20, v226, v3, vcc
	v_cmp_le_i32_e32 vcc, v24, v206
	s_nop 1
	v_cndmask_b32_e32 v60, v226, v2, vcc
	v_max3_f32 v2, v17, v60, v20
	v_max3_f32 v2, v2, v23, v22
	v_max3_f32 v2, v2, v56, v29
	v_max3_f32 v17, v2, v47, v43
	v_pk_mul_f32 v[2:3], v[4:5], s[8:9] op_sel_hi:[1,0]
	v_or_b32_e32 v4, 0x6af, v67
	v_or_b32_e32 v5, 0x69f, v67
	v_cmp_le_i32_e32 vcc, v4, v206
	v_or_b32_e32 v4, 0x79f, v67
	s_nop 0
	v_cndmask_b32_e32 v32, v226, v3, vcc
	v_cmp_le_i32_e32 vcc, v5, v206
	v_or_b32_e32 v3, 31, v72
	s_nop 0
	v_cndmask_b32_e32 v48, v226, v2, vcc
	v_or_b32_e32 v2, 0x62f, v67
	v_cmp_le_i32_e32 vcc, v2, v206
	s_nop 1
	v_cndmask_b32_e32 v28, v226, v1, vcc
	v_cmp_le_i32_e32 vcc, v3, v206
	v_or_b32_e32 v3, 0x7af, v67
	s_nop 0
	v_cndmask_b32_e32 v33, v226, v0, vcc
	v_max3_f32 v0, v17, v33, v28
	v_max3_f32 v0, v0, v42, v39
	v_max3_f32 v0, v0, v48, v32
	v_max3_f32 v2, v0, v38, v35
	v_pk_mul_f32 v[0:1], v[12:13], s[8:9] op_sel_hi:[1,0]
	v_cmp_le_i32_e32 vcc, v3, v206
	v_or_b32_e32 v3, 0x72f, v67
	s_nop 0
	v_cndmask_b32_e32 v25, v226, v1, vcc
	v_cmp_le_i32_e32 vcc, v4, v206
	v_or_b32_e32 v4, 0x71f, v67
	s_nop 0
	v_cndmask_b32_e32 v37, v226, v0, vcc
	v_pk_mul_f32 v[0:1], v[8:9], s[8:9] op_sel_hi:[1,0]
	v_cmp_le_i32_e32 vcc, v3, v206
	s_nop 1
	v_cndmask_b32_e32 v44, v226, v1, vcc
	v_cmp_le_i32_e32 vcc, v4, v206
	s_nop 1
	v_cndmask_b32_e32 v45, v226, v0, vcc
	v_max3_f32 v0, v2, v45, v44
	v_max3_f32 v0, v0, v31, v30
	v_max3_f32 v0, v0, v37, v25
	v_max3_f32 v0, v0, v27, v26
	ds_bpermute_b32 v1, v236, v0
	v_cmp_neq_f32_e32 vcc, s0, v7
	s_waitcnt lgkmcnt(0)
	v_max_f32_e32 v1, v1, v1
	v_max_f32_e32 v24, v0, v1
	v_sub_f32_e32 v1, v7, v24
	v_sub_f32_e32 v0, v6, v24
	v_mul_f32_e32 v1, 0x3fb8aa3b, v1
	v_mul_f32_e32 v0, 0x3fb8aa3b, v0
	v_exp_f32_e32 v1, v1
	v_sub_f32_e32 v3, v50, v24
	v_exp_f32_e32 v0, v0
	v_mul_f32_e32 v3, 0x3fb8aa3b, v3
	v_exp_f32_e32 v3, v3
	v_cndmask_b32_e32 v1, 0, v1, vcc
	v_cmp_neq_f32_e32 vcc, s0, v6
	v_sub_f32_e32 v5, v54, v24
	v_mul_f32_e32 v5, 0x3fb8aa3b, v5
	v_cndmask_b32_e32 v0, 0, v0, vcc
	v_cmp_neq_f32_e32 vcc, s0, v50
	v_add_f32_e32 v2, 0, v0
	v_add_f32_e32 v2, v1, v2
	v_cndmask_b32_e32 v34, 0, v3, vcc
	v_sub_f32_e32 v3, v51, v24
	v_mul_f32_e32 v3, 0x3fb8aa3b, v3
	v_exp_f32_e32 v3, v3
	v_cmp_neq_f32_e32 vcc, s0, v51
	v_add_f32_e32 v2, v34, v2
	v_exp_f32_e32 v5, v5
	v_cndmask_b32_e32 v40, 0, v3, vcc
	v_sub_f32_e32 v3, v73, v24
	v_add_f32_e32 v4, v40, v2
	v_sub_f32_e32 v2, v46, v24
	v_mul_f32_e32 v3, 0x3fb8aa3b, v3
	v_mul_f32_e32 v2, 0x3fb8aa3b, v2
	v_exp_f32_e32 v3, v3
	v_exp_f32_e32 v2, v2
	v_cmp_neq_f32_e32 vcc, s0, v73
	v_sub_f32_e32 v7, v82, v24
	v_mul_f32_e32 v7, 0x3fb8aa3b, v7
	v_cndmask_b32_e32 v3, 0, v3, vcc
	v_cmp_neq_f32_e32 vcc, s0, v46
	v_exp_f32_e32 v7, v7
	v_sub_f32_e32 v9, v62, v24
	v_cndmask_b32_e32 v2, 0, v2, vcc
	v_cmp_neq_f32_e32 vcc, s0, v54
	v_add_f32_e32 v4, v2, v4
	v_add_f32_e32 v4, v3, v4
	v_cndmask_b32_e32 v36, 0, v5, vcc
	v_sub_f32_e32 v5, v80, v24
	v_mul_f32_e32 v5, 0x3fb8aa3b, v5
	v_exp_f32_e32 v5, v5
	v_cmp_neq_f32_e32 vcc, s0, v80
	v_add_f32_e32 v4, v36, v4
	v_mul_f32_e32 v9, 0x3fb8aa3b, v9
	v_cndmask_b32_e32 v46, 0, v5, vcc
	v_sub_f32_e32 v5, v57, v24
	v_add_f32_e32 v6, v46, v4
	v_sub_f32_e32 v4, v81, v24
	v_mul_f32_e32 v5, 0x3fb8aa3b, v5
	v_mul_f32_e32 v4, 0x3fb8aa3b, v4
	v_exp_f32_e32 v5, v5
	v_exp_f32_e32 v4, v4
	v_cmp_neq_f32_e32 vcc, s0, v57
	v_exp_f32_e32 v9, v9
	v_sub_f32_e32 v13, v11, v24
	v_cndmask_b32_e32 v5, 0, v5, vcc
	v_cmp_neq_f32_e32 vcc, s0, v81
	v_mul_f32_e32 v13, 0x3fb8aa3b, v13
	v_exp_f32_e32 v13, v13
	v_cndmask_b32_e32 v4, 0, v4, vcc
	v_cmp_neq_f32_e32 vcc, s0, v82
	v_add_f32_e32 v6, v4, v6
	v_add_f32_e32 v6, v5, v6
	v_cndmask_b32_e32 v41, 0, v7, vcc
	v_sub_f32_e32 v7, v83, v24
	v_mul_f32_e32 v7, 0x3fb8aa3b, v7
	v_exp_f32_e32 v7, v7
	v_cmp_neq_f32_e32 vcc, s0, v83
	v_add_f32_e32 v6, v41, v6
	s_nop 0
	v_cndmask_b32_e32 v49, 0, v7, vcc
	v_sub_f32_e32 v7, v74, v24
	v_add_f32_e32 v8, v49, v6
	v_sub_f32_e32 v6, v75, v24
	v_mul_f32_e32 v7, 0x3fb8aa3b, v7
	v_mul_f32_e32 v6, 0x3fb8aa3b, v6
	v_exp_f32_e32 v7, v7
	v_exp_f32_e32 v6, v6
	v_cmp_neq_f32_e32 vcc, s0, v74
	s_nop 1
	v_cndmask_b32_e32 v7, 0, v7, vcc
	v_cmp_neq_f32_e32 vcc, s0, v75
	s_nop 1
	v_cndmask_b32_e32 v6, 0, v6, vcc
	v_cmp_neq_f32_e32 vcc, s0, v62
	v_add_f32_e32 v8, v6, v8
	v_add_f32_e32 v8, v7, v8
	v_cndmask_b32_e32 v50, 0, v9, vcc
	v_sub_f32_e32 v9, v84, v24
	v_mul_f32_e32 v9, 0x3fb8aa3b, v9
	v_exp_f32_e32 v9, v9
	v_cmp_neq_f32_e32 vcc, s0, v84
	v_add_f32_e32 v8, v50, v8
	s_nop 0
	v_cndmask_b32_e32 v54, 0, v9, vcc
	v_sub_f32_e32 v9, v78, v24
	v_add_f32_e32 v12, v54, v8
	v_sub_f32_e32 v8, v79, v24
	v_mul_f32_e32 v9, 0x3fb8aa3b, v9
	v_mul_f32_e32 v8, 0x3fb8aa3b, v8
	v_exp_f32_e32 v9, v9
	v_exp_f32_e32 v8, v8
	v_cmp_neq_f32_e32 vcc, s0, v78
	s_nop 1
	v_cndmask_b32_e32 v9, 0, v9, vcc
	v_cmp_neq_f32_e32 vcc, s0, v79
	s_nop 1
	v_cndmask_b32_e32 v8, 0, v8, vcc
	v_add_f32_e32 v12, v8, v12
	v_cmp_neq_f32_e32 vcc, s0, v11
	v_add_f32_e32 v12, v9, v12
	s_nop 0
	v_cndmask_b32_e32 v51, 0, v13, vcc
	v_add_f32_e32 v11, v51, v12
	v_sub_f32_e32 v12, v10, v24
	v_mul_f32_e32 v12, 0x3fb8aa3b, v12
	v_exp_f32_e32 v12, v12
	v_cmp_neq_f32_e32 vcc, s0, v10
	v_sub_f32_e32 v10, v77, v24
	v_mul_f32_e32 v10, 0x3fb8aa3b, v10
	v_cndmask_b32_e32 v57, 0, v12, vcc
	v_add_f32_e32 v12, v57, v11
	v_sub_f32_e32 v11, v76, v24
	v_mul_f32_e32 v11, 0x3fb8aa3b, v11
	v_exp_f32_e32 v11, v11
	v_sub_f32_e32 v13, v55, v24
	v_exp_f32_e32 v10, v10
	v_mul_f32_e32 v13, 0x3fb8aa3b, v13
	v_exp_f32_e32 v13, v13
	v_cmp_neq_f32_e32 vcc, s0, v76
	s_nop 1
	v_cndmask_b32_e32 v11, 0, v11, vcc
	v_cmp_neq_f32_e32 vcc, s0, v77
	s_nop 1
	v_cndmask_b32_e32 v10, 0, v10, vcc
	v_cmp_neq_f32_e32 vcc, s0, v55
	v_add_f32_e32 v12, v10, v12
	v_add_f32_e32 v12, v11, v12
	v_cndmask_b32_e32 v55, 0, v13, vcc
	v_sub_f32_e32 v13, v58, v24
	v_mul_f32_e32 v13, 0x3fb8aa3b, v13
	v_exp_f32_e32 v13, v13
	v_cmp_neq_f32_e32 vcc, s0, v58
	v_add_f32_e32 v12, v55, v12
	v_sub_f32_e32 v58, v15, v24
	v_cndmask_b32_e32 v62, 0, v13, vcc
	v_sub_f32_e32 v13, v85, v24
	v_add_f32_e32 v17, v62, v12
	v_sub_f32_e32 v12, v86, v24
	v_mul_f32_e32 v13, 0x3fb8aa3b, v13
	v_mul_f32_e32 v12, 0x3fb8aa3b, v12
	v_exp_f32_e32 v13, v13
	v_exp_f32_e32 v12, v12
	v_mul_f32_e32 v58, 0x3fb8aa3b, v58
	v_cmp_neq_f32_e32 vcc, s0, v85
	v_exp_f32_e32 v58, v58
	s_nop 0
	v_cndmask_b32_e32 v13, 0, v13, vcc
	v_cmp_neq_f32_e32 vcc, s0, v86
	s_nop 1
	v_cndmask_b32_e32 v12, 0, v12, vcc
	v_add_f32_e32 v17, v12, v17
	v_cmp_neq_f32_e32 vcc, s0, v15
	v_add_f32_e32 v17, v13, v17
	s_nop 0
	v_cndmask_b32_e32 v58, 0, v58, vcc
	v_add_f32_e32 v15, v58, v17
	v_sub_f32_e32 v17, v14, v24
	v_mul_f32_e32 v17, 0x3fb8aa3b, v17
	v_exp_f32_e32 v17, v17
	v_cmp_neq_f32_e32 vcc, s0, v14
	v_sub_f32_e32 v14, v70, v24
	v_mul_f32_e32 v14, 0x3fb8aa3b, v14
	v_cndmask_b32_e32 v67, 0, v17, vcc
	v_add_f32_e32 v17, v67, v15
	v_sub_f32_e32 v15, v69, v24
	v_mul_f32_e32 v15, 0x3fb8aa3b, v15
	v_exp_f32_e32 v15, v15
	v_cmp_neq_f32_e32 vcc, s0, v69
	v_sub_f32_e32 v69, v61, v24
	v_exp_f32_e32 v14, v14
	v_mul_f32_e32 v69, 0x3fb8aa3b, v69
	v_exp_f32_e32 v69, v69
	v_cndmask_b32_e32 v15, 0, v15, vcc
	v_cmp_neq_f32_e32 vcc, s0, v70
	s_nop 1
	v_cndmask_b32_e32 v14, 0, v14, vcc
	v_cmp_neq_f32_e32 vcc, s0, v61
	v_add_f32_e32 v17, v14, v17
	v_add_f32_e32 v17, v15, v17
	v_cndmask_b32_e32 v61, 0, v69, vcc
	v_sub_f32_e32 v69, v59, v24
	v_mul_f32_e32 v69, 0x3fb8aa3b, v69
	v_exp_f32_e32 v69, v69
	v_cmp_neq_f32_e32 vcc, s0, v59
	v_add_f32_e32 v17, v61, v17
	s_nop 0
	v_cndmask_b32_e32 v69, 0, v69, vcc
	v_add_f32_e32 v59, v69, v17
	v_sub_f32_e32 v17, v68, v24
	v_mul_f32_e32 v17, 0x3fb8aa3b, v17
	v_exp_f32_e32 v70, v17
	v_sub_f32_e32 v17, v16, v24
	v_mul_f32_e32 v17, 0x3fb8aa3b, v17
	v_exp_f32_e32 v17, v17
	v_cmp_neq_f32_e32 vcc, s0, v16
	s_nop 1
	v_cndmask_b32_e32 v17, 0, v17, vcc
	v_cmp_neq_f32_e32 vcc, s0, v68
	s_nop 1
	v_cndmask_b32_e32 v16, 0, v70, vcc
	v_add_f32_e32 v59, v16, v59
	v_add_f32_e32 v68, v17, v59
	v_sub_f32_e32 v59, v19, v24
	v_mul_f32_e32 v59, 0x3fb8aa3b, v59
	v_exp_f32_e32 v59, v59
	v_cmp_neq_f32_e32 vcc, s0, v19
	s_nop 1
	v_cndmask_b32_e32 v59, 0, v59, vcc
	v_add_f32_e32 v19, v59, v68
	v_sub_f32_e32 v68, v18, v24
	v_mul_f32_e32 v68, 0x3fb8aa3b, v68
	v_exp_f32_e32 v68, v68
	v_cmp_neq_f32_e32 vcc, s0, v18
	v_sub_f32_e32 v18, v63, v24
	v_mul_f32_e32 v18, 0x3fb8aa3b, v18
	v_cndmask_b32_e32 v68, 0, v68, vcc
	v_add_f32_e32 v70, v68, v19
	v_sub_f32_e32 v19, v21, v24
	v_mul_f32_e32 v19, 0x3fb8aa3b, v19
	v_exp_f32_e32 v19, v19
	v_cmp_neq_f32_e32 vcc, s0, v21
	v_exp_f32_e32 v18, v18
	s_nop 0
	v_cndmask_b32_e32 v19, 0, v19, vcc
	v_cmp_neq_f32_e32 vcc, s0, v63
	v_sub_f32_e32 v63, v53, v24
	v_mul_f32_e32 v63, 0x3fb8aa3b, v63
	v_exp_f32_e32 v63, v63
	v_cndmask_b32_e32 v18, 0, v18, vcc
	v_cmp_neq_f32_e32 vcc, s0, v53
	v_add_f32_e32 v21, v18, v70
	v_add_f32_e32 v21, v19, v21
	v_cndmask_b32_e32 v53, 0, v63, vcc
	v_sub_f32_e32 v63, v52, v24
	v_mul_f32_e32 v63, 0x3fb8aa3b, v63
	v_exp_f32_e32 v63, v63
	v_cmp_neq_f32_e32 vcc, s0, v52
	v_add_f32_e32 v21, v53, v21
	s_nop 0
	v_cndmask_b32_e32 v52, 0, v63, vcc
	v_add_f32_e32 v63, v52, v21
	v_sub_f32_e32 v21, v60, v24
	v_mul_f32_e32 v21, 0x3fb8aa3b, v21
	v_exp_f32_e32 v70, v21
	v_sub_f32_e32 v21, v20, v24
	v_mul_f32_e32 v21, 0x3fb8aa3b, v21
	v_exp_f32_e32 v21, v21
	v_cmp_neq_f32_e32 vcc, s0, v20
	s_nop 1
	v_cndmask_b32_e32 v21, 0, v21, vcc
	v_cmp_neq_f32_e32 vcc, s0, v60
	s_nop 1
	v_cndmask_b32_e32 v20, 0, v70, vcc
	v_add_f32_e32 v60, v20, v63
	v_sub_f32_e32 v63, v23, v24
	v_mul_f32_e32 v63, 0x3fb8aa3b, v63
	v_exp_f32_e32 v63, v63
	v_cmp_neq_f32_e32 vcc, s0, v23
	v_add_f32_e32 v60, v21, v60
	s_nop 0
	v_cndmask_b32_e32 v63, 0, v63, vcc
	v_add_f32_e32 v23, v63, v60
	v_sub_f32_e32 v60, v22, v24
	v_mul_f32_e32 v60, 0x3fb8aa3b, v60
	v_exp_f32_e32 v60, v60
	v_cmp_neq_f32_e32 vcc, s0, v22
	v_sub_f32_e32 v22, v56, v24
	v_mul_f32_e32 v22, 0x3fb8aa3b, v22
	v_cndmask_b32_e32 v60, 0, v60, vcc
	v_add_f32_e32 v70, v60, v23
	v_sub_f32_e32 v23, v29, v24
	v_mul_f32_e32 v23, 0x3fb8aa3b, v23
	v_exp_f32_e32 v23, v23
	v_cmp_neq_f32_e32 vcc, s0, v29
	v_exp_f32_e32 v22, v22
	s_nop 0
	v_cndmask_b32_e32 v23, 0, v23, vcc
	v_cmp_neq_f32_e32 vcc, s0, v56
	v_sub_f32_e32 v56, v47, v24
	v_mul_f32_e32 v56, 0x3fb8aa3b, v56
	v_exp_f32_e32 v56, v56
	v_cndmask_b32_e32 v22, 0, v22, vcc
	v_cmp_neq_f32_e32 vcc, s0, v47
	v_add_f32_e32 v29, v22, v70
	v_add_f32_e32 v29, v23, v29
	v_cndmask_b32_e32 v47, 0, v56, vcc
	v_sub_f32_e32 v56, v43, v24
	v_mul_f32_e32 v56, 0x3fb8aa3b, v56
	v_exp_f32_e32 v56, v56
	v_cmp_neq_f32_e32 vcc, s0, v43
	v_add_f32_e32 v29, v47, v29
	s_nop 0
	v_cndmask_b32_e32 v56, 0, v56, vcc
	v_add_f32_e32 v43, v56, v29
	v_sub_f32_e32 v29, v33, v24
	v_mul_f32_e32 v29, 0x3fb8aa3b, v29
	v_exp_f32_e32 v70, v29
	v_sub_f32_e32 v29, v28, v24
	v_mul_f32_e32 v29, 0x3fb8aa3b, v29
	v_exp_f32_e32 v29, v29
	v_cmp_neq_f32_e32 vcc, s0, v28
	s_nop 1
	v_cndmask_b32_e32 v29, 0, v29, vcc
	v_cmp_neq_f32_e32 vcc, s0, v33
	s_nop 1
	v_cndmask_b32_e32 v28, 0, v70, vcc
	v_add_f32_e32 v33, v28, v43
	v_sub_f32_e32 v43, v42, v24
	v_mul_f32_e32 v43, 0x3fb8aa3b, v43
	v_cmp_neq_f32_e32 vcc, s0, v42
	v_sub_f32_e32 v42, v39, v24
	v_exp_f32_e32 v43, v43
	v_mul_f32_e32 v42, 0x3fb8aa3b, v42
	v_exp_f32_e32 v42, v42
	v_add_f32_e32 v33, v29, v33
	v_cndmask_b32_e32 v78, 0, v43, vcc
	v_cmp_neq_f32_e32 vcc, s0, v39
	v_add_f32_e32 v33, v78, v33
	v_sub_f32_e32 v43, v31, v24
	v_cndmask_b32_e32 v79, 0, v42, vcc
	v_add_f32_e32 v39, v79, v33
	v_sub_f32_e32 v33, v48, v24
	v_mul_f32_e32 v33, 0x3fb8aa3b, v33
	v_exp_f32_e32 v42, v33
	v_sub_f32_e32 v33, v32, v24
	v_mul_f32_e32 v33, 0x3fb8aa3b, v33
	v_exp_f32_e32 v33, v33
	v_cmp_neq_f32_e32 vcc, s0, v32
	v_mul_f32_e32 v43, 0x3fb8aa3b, v43
	v_exp_f32_e32 v43, v43
	v_cndmask_b32_e32 v33, 0, v33, vcc
	v_cmp_neq_f32_e32 vcc, s0, v48
	s_nop 1
	v_cndmask_b32_e32 v32, 0, v42, vcc
	v_sub_f32_e32 v42, v38, v24
	v_mul_f32_e32 v42, 0x3fb8aa3b, v42
	v_exp_f32_e32 v42, v42
	v_add_f32_e32 v39, v32, v39
	v_cmp_neq_f32_e32 vcc, s0, v38
	v_add_f32_e32 v39, v33, v39
	s_nop 0
	v_cndmask_b32_e32 v80, 0, v42, vcc
	v_add_f32_e32 v38, v80, v39
	v_sub_f32_e32 v39, v35, v24
	v_mul_f32_e32 v39, 0x3fb8aa3b, v39
	v_exp_f32_e32 v39, v39
	v_cmp_neq_f32_e32 vcc, s0, v35
	s_nop 1
	v_cndmask_b32_e32 v35, 0, v39, vcc
	v_sub_f32_e32 v39, v44, v24
	v_add_f32_e32 v42, v35, v38
	v_sub_f32_e32 v38, v45, v24
	v_mul_f32_e32 v39, 0x3fb8aa3b, v39
	v_mul_f32_e32 v38, 0x3fb8aa3b, v38
	v_exp_f32_e32 v39, v39
	v_exp_f32_e32 v38, v38
	v_cmp_neq_f32_e32 vcc, s0, v44
	s_nop 1
	v_cndmask_b32_e32 v39, 0, v39, vcc
	v_cmp_neq_f32_e32 vcc, s0, v45
	s_nop 1
	v_cndmask_b32_e32 v38, 0, v38, vcc
	v_add_f32_e32 v42, v38, v42
	v_cmp_neq_f32_e32 vcc, s0, v31
	v_add_f32_e32 v42, v39, v42
	s_nop 0
	v_cndmask_b32_e32 v45, 0, v43, vcc
	v_add_f32_e32 v31, v45, v42
	v_sub_f32_e32 v42, v30, v24
	v_mul_f32_e32 v42, 0x3fb8aa3b, v42
	v_exp_f32_e32 v42, v42
	v_cmp_neq_f32_e32 vcc, s0, v30
	s_nop 1
	v_cndmask_b32_e32 v81, 0, v42, vcc
	v_sub_f32_e32 v42, v25, v24
	v_add_f32_e32 v30, v81, v31
	v_sub_f32_e32 v31, v37, v24
	v_mul_f32_e32 v42, 0x3fb8aa3b, v42
	v_mul_f32_e32 v31, 0x3fb8aa3b, v31
	v_exp_f32_e32 v42, v42
	v_exp_f32_e32 v31, v31
	v_cmp_neq_f32_e32 vcc, s0, v25
	s_nop 1
	v_cndmask_b32_e32 v43, 0, v42, vcc
	v_cmp_neq_f32_e32 vcc, s0, v37
	s_nop 1
	v_cndmask_b32_e32 v42, 0, v31, vcc
	v_add_f32_e32 v25, v42, v30
	v_sub_f32_e32 v30, v27, v24
	v_mul_f32_e32 v30, 0x3fb8aa3b, v30
	v_sub_f32_e32 v24, v26, v24
	v_exp_f32_e32 v30, v30
	v_mul_f32_e32 v24, 0x3fb8aa3b, v24
	v_exp_f32_e32 v24, v24
	v_cmp_neq_f32_e32 vcc, s0, v27
	v_add_f32_e32 v25, v43, v25
	s_nop 0
	v_cndmask_b32_e32 v37, 0, v30, vcc
	v_cmp_neq_f32_e32 vcc, s0, v26
	v_add_f32_e32 v25, v37, v25
	s_nop 0
	v_cndmask_b32_e32 v82, 0, v24, vcc
	v_add_f32_e32 v24, v82, v25
	ds_bpermute_b32 v25, v236, v24
	s_waitcnt lgkmcnt(0)
	v_add_f32_e32 v24, v24, v25
	v_max_f32_e32 v24, 0xda24260, v24
	v_div_scale_f32 v25, s[0:1], v24, v24, 1.0
	v_rcp_f32_e32 v26, v25
	s_nop 0
	v_fma_f32 v27, -v25, v26, 1.0
	v_fmac_f32_e32 v26, v27, v26
	v_div_scale_f32 v27, vcc, 1.0, v24, 1.0
	v_mul_f32_e32 v30, v27, v26
	v_fma_f32 v31, -v25, v30, v27
	v_fmac_f32_e32 v30, v31, v26
	v_fma_f32 v25, -v25, v30, v27
	v_div_fmas_f32 v25, v25, v26, v30
	v_div_fixup_f32 v44, v25, v24, 1.0
	v_pk_mul_f32 v[70:71], v[0:1], v[44:45] op_sel_hi:[1,0]
	v_mul_f32_e32 v40, v40, v44
	v_pk_mul_f32 v[74:75], v[4:5], v[44:45] op_sel_hi:[1,0]
	v_pk_mul_f32 v[4:5], v[28:29], v[44:45] op_sel_hi:[1,0]
	v_lshl_or_b32 v28, v66, 5, v150
	v_pk_mul_f32 v[72:73], v[2:3], v[44:45] op_sel_hi:[1,0]
	v_mul_f32_e32 v46, v46, v44
	v_pk_mul_f32 v[76:77], v[6:7], v[44:45] op_sel_hi:[1,0]
	v_pk_mul_f32 v[6:7], v[32:33], v[44:45] op_sel_hi:[1,0]
	v_lshl_add_u32 v28, v28, 5, v28
	v_add_f32_e32 v29, v70, v71
	v_fma_f32 v32, v34, v44, v40
	v_add_f32_e32 v29, v29, v32
	v_add_lshl_u32 v28, v28, v64, 2
	v_add_f32_e32 v32, v72, v73
	v_fma_f32 v33, v36, v44, v46
	v_mul_f32_e32 v97, v49, v44
	v_add_f32_e32 v32, v32, v33
	v_add_u32_e32 v33, 0x9000, v28
	v_mul_f32_e32 v54, v54, v44
	ds_write2_b32 v33, v29, v32 offset1:2
	v_add_f32_e32 v29, v74, v75
	v_fma_f32 v32, v41, v44, v97
	v_mul_f32_e32 v83, v34, v44
	v_add_f32_e32 v29, v29, v32
	v_add_f32_e32 v32, v76, v77
	v_fma_f32 v34, v50, v44, v54
	v_pk_mul_f32 v[30:31], v[8:9], v[44:45] op_sel_hi:[1,0]
	v_mul_f32_e32 v100, v57, v44
	v_add_u32_e32 v28, 0xd000, v28
	v_add_f32_e32 v32, v32, v34
	v_pk_mul_f32 v[48:49], v[10:11], v[44:45] op_sel_hi:[1,0]
	v_mul_f32_e32 v62, v62, v44
	ds_write2_b32 v28, v40, v46 offset0:128 offset1:130
	ds_write2_b32 v33, v29, v32 offset0:4 offset1:6
	ds_write2_b32 v28, v97, v54 offset0:132 offset1:134
	v_add_f32_e32 v29, v30, v31
	v_fma_f32 v32, v51, v44, v100
	v_add_f32_e32 v29, v29, v32
	v_add_f32_e32 v32, v48, v49
	v_fma_f32 v34, v55, v44, v62
	v_pk_mul_f32 v[24:25], v[12:13], v[44:45] op_sel_hi:[1,0]
	v_mul_f32_e32 v67, v67, v44
	v_add_f32_e32 v32, v32, v34
	v_pk_mul_f32 v[26:27], v[14:15], v[44:45] op_sel_hi:[1,0]
	v_mul_f32_e32 v69, v69, v44
	ds_write2_b32 v33, v29, v32 offset0:8 offset1:10
	ds_write2_b32 v28, v100, v62 offset0:136 offset1:138
	v_add_f32_e32 v29, v24, v25
	v_fma_f32 v32, v58, v44, v67
	v_add_f32_e32 v29, v29, v32
	v_add_f32_e32 v32, v26, v27
	v_fma_f32 v34, v61, v44, v69
	v_pk_mul_f32 v[12:13], v[16:17], v[44:45] op_sel_hi:[1,0]
	v_mul_f32_e32 v68, v68, v44
	v_add_f32_e32 v32, v32, v34
	v_pk_mul_f32 v[14:15], v[18:19], v[44:45] op_sel_hi:[1,0]
	v_mul_f32_e32 v106, v52, v44
	ds_write2_b32 v33, v29, v32 offset0:12 offset1:14
	ds_write2_b32 v28, v67, v69 offset0:140 offset1:142
	v_add_f32_e32 v29, v12, v13
	v_fma_f32 v32, v59, v44, v68
	v_add_f32_e32 v29, v29, v32
	v_add_f32_e32 v32, v14, v15
	v_fma_f32 v34, v53, v44, v106
	v_pk_mul_f32 v[8:9], v[20:21], v[44:45] op_sel_hi:[1,0]
	v_mul_f32_e32 v108, v60, v44
	v_add_f32_e32 v32, v32, v34
	v_pk_mul_f32 v[10:11], v[22:23], v[44:45] op_sel_hi:[1,0]
	v_mul_f32_e32 v110, v56, v44
	ds_write2_b32 v33, v29, v32 offset0:16 offset1:18
	ds_write2_b32 v28, v68, v106 offset0:144 offset1:146
	v_add_f32_e32 v29, v8, v9
	v_fma_f32 v32, v63, v44, v108
	v_add_f32_e32 v29, v29, v32
	v_add_f32_e32 v32, v10, v11
	v_fma_f32 v34, v47, v44, v110
	v_mul_f32_e32 v21, v79, v44
	v_add_f32_e32 v32, v32, v34
	v_mul_f32_e32 v23, v35, v44
	ds_write2_b32 v33, v29, v32 offset0:20 offset1:22
	ds_write2_b32 v28, v108, v110 offset0:148 offset1:150
	v_add_f32_e32 v29, v4, v5
	v_fma_f32 v32, v78, v44, v21
	v_add_f32_e32 v29, v29, v32
	v_add_f32_e32 v32, v6, v7
	v_fma_f32 v34, v80, v44, v23
	v_pk_mul_f32 v[0:1], v[38:39], v[44:45] op_sel_hi:[1,0]
	v_mul_f32_e32 v17, v81, v44
	v_add_f32_e32 v32, v32, v34
	v_pk_mul_f32 v[2:3], v[42:43], v[44:45] op_sel_hi:[1,0]
	v_mul_f32_e32 v19, v82, v44
	ds_write2_b32 v33, v29, v32 offset0:24 offset1:26
	ds_write2_b32 v28, v21, v23 offset0:152 offset1:154
	v_add_f32_e32 v29, v0, v1
	v_fma_f32 v32, v45, v44, v17
	v_add_f32_e32 v29, v29, v32
	v_add_f32_e32 v32, v2, v3
	v_fma_f32 v34, v37, v44, v19
	v_add_f32_e32 v32, v32, v34
	ds_write2_b32 v33, v29, v32 offset0:28 offset1:30
	ds_write2_b32 v28, v17, v19 offset0:156 offset1:158
	v_mad_u32_u24 v28, v150, s10, v235
	v_mul_f32_e32 v107, v63, v44
	v_add_u32_e32 v63, 0x4800, v28
	v_add_u32_e32 v66, 0x6800, v28
	v_mul_f32_e32 v84, v36, v44
	v_mul_f32_e32 v96, v41, v44
	v_mul_f32_e32 v18, v37, v44
	v_cvt_pk_bf16_f32 v33, v83, v40
	ds_read2_b64 v[36:39], v63 offset1:2
	ds_read2_b64 v[40:43], v66 offset0:32 offset1:34
	v_cvt_pk_bf16_f32 v32, v70, v71
	v_cvt_pk_bf16_f32 v34, v72, v73
	v_cvt_pk_bf16_f32 v35, v84, v46
	v_mul_f32_e32 v98, v50, v44
	v_mul_f32_e32 v99, v51, v44
	v_mul_f32_e32 v101, v55, v44
	v_mul_f32_e32 v102, v58, v44
	v_mul_f32_e32 v103, v61, v44
	v_mul_f32_e32 v104, v59, v44
	v_mul_f32_e32 v105, v53, v44
	v_mul_f32_e32 v109, v47, v44
	v_mul_f32_e32 v20, v78, v44
	v_mul_f32_e32 v22, v80, v44
	v_mul_f32_e32 v16, v45, v44
	s_waitcnt lgkmcnt(1)
	v_mfma_f32_32x32x16_bf16 v[80:95], v[36:39], v[32:35], 0
	s_waitcnt lgkmcnt(0)
	v_mfma_f32_32x32x16_bf16 v[32:47], v[40:43], v[32:35], 0
	v_cvt_pk_bf16_f32 v53, v98, v54
	ds_read2_b64 v[54:57], v63 offset0:4 offset1:6
	ds_read2_b64 v[58:61], v66 offset0:36 offset1:38
	v_cvt_pk_bf16_f32 v50, v74, v75
	v_cvt_pk_bf16_f32 v51, v96, v97
	v_cvt_pk_bf16_f32 v52, v76, v77
	s_nop 0
	s_nop 0
	s_waitcnt lgkmcnt(1)
	v_mfma_f32_32x32x16_bf16 v[80:95], v[54:57], v[50:53], v[80:95]
	s_waitcnt lgkmcnt(0)
	v_mfma_f32_32x32x16_bf16 v[32:47], v[58:61], v[50:53], v[32:47]
	v_cvt_pk_bf16_f32 v28, v30, v31
	v_cvt_pk_bf16_f32 v30, v48, v49
	ds_read2_b64 v[48:51], v63 offset0:8 offset1:10
	ds_read2_b64 v[52:55], v66 offset0:40 offset1:42
	v_cvt_pk_bf16_f32 v29, v99, v100
	v_cvt_pk_bf16_f32 v31, v101, v62
	s_nop 0
	s_nop 0
	s_waitcnt lgkmcnt(1)
	v_mfma_f32_32x32x16_bf16 v[80:95], v[48:51], v[28:31], v[80:95]
	s_waitcnt lgkmcnt(0)
	v_mfma_f32_32x32x16_bf16 v[32:47], v[52:55], v[28:31], v[32:47]
	ds_read2_b64 v[28:31], v63 offset0:12 offset1:14
	ds_read2_b64 v[48:51], v66 offset0:44 offset1:46
	v_cvt_pk_bf16_f32 v24, v24, v25
	v_cvt_pk_bf16_f32 v25, v102, v67
	v_cvt_pk_bf16_f32 v26, v26, v27
	v_cvt_pk_bf16_f32 v27, v103, v69
	s_nop 0
	s_nop 0
	s_waitcnt lgkmcnt(1)
	v_mfma_f32_32x32x16_bf16 v[80:95], v[28:31], v[24:27], v[80:95]
	s_waitcnt lgkmcnt(0)
	v_mfma_f32_32x32x16_bf16 v[32:47], v[48:51], v[24:27], v[32:47]
	ds_read2_b64 v[24:27], v63 offset0:16 offset1:18
	ds_read2_b64 v[28:31], v66 offset0:48 offset1:50
	v_cvt_pk_bf16_f32 v12, v12, v13
	v_cvt_pk_bf16_f32 v13, v104, v68
	v_cvt_pk_bf16_f32 v14, v14, v15
	v_cvt_pk_bf16_f32 v15, v105, v106
	s_nop 0
	s_nop 0
	s_waitcnt lgkmcnt(1)
	v_mfma_f32_32x32x16_bf16 v[80:95], v[24:27], v[12:15], v[80:95]
	s_waitcnt lgkmcnt(0)
	v_mfma_f32_32x32x16_bf16 v[32:47], v[28:31], v[12:15], v[32:47]
	ds_read2_b64 v[12:15], v63 offset0:20 offset1:22
	ds_read2_b64 v[24:27], v66 offset0:52 offset1:54
	v_cvt_pk_bf16_f32 v8, v8, v9
	v_cvt_pk_bf16_f32 v9, v107, v108
	v_cvt_pk_bf16_f32 v10, v10, v11
	v_cvt_pk_bf16_f32 v11, v109, v110
	s_nop 0
	s_nop 0
	s_waitcnt lgkmcnt(1)
	v_mfma_f32_32x32x16_bf16 v[80:95], v[12:15], v[8:11], v[80:95]
	s_waitcnt lgkmcnt(0)
	v_mfma_f32_32x32x16_bf16 v[32:47], v[24:27], v[8:11], v[32:47]
	ds_read2_b64 v[8:11], v63 offset0:24 offset1:26
	ds_read2_b64 v[12:15], v66 offset0:56 offset1:58
	v_cvt_pk_bf16_f32 v4, v4, v5
	v_cvt_pk_bf16_f32 v5, v20, v21
	v_cvt_pk_bf16_f32 v6, v6, v7
	v_cvt_pk_bf16_f32 v7, v22, v23
	s_nop 0
	s_nop 0
	s_waitcnt lgkmcnt(1)
	v_mfma_f32_32x32x16_bf16 v[80:95], v[8:11], v[4:7], v[80:95]
	s_waitcnt lgkmcnt(0)
	v_mfma_f32_32x32x16_bf16 v[32:47], v[12:15], v[4:7], v[32:47]
	ds_read2_b64 v[4:7], v63 offset0:28 offset1:30
	ds_read2_b64 v[8:11], v66 offset0:60 offset1:62
	v_cvt_pk_bf16_f32 v0, v0, v1
	v_cvt_pk_bf16_f32 v1, v16, v17
	v_cvt_pk_bf16_f32 v2, v2, v3
	v_cvt_pk_bf16_f32 v3, v18, v19
	s_nop 0
	s_nop 0
	s_waitcnt lgkmcnt(1)
	v_mfma_f32_32x32x16_bf16 v[80:95], v[4:7], v[0:3], v[80:95]
	s_waitcnt lgkmcnt(0)
	v_mfma_f32_32x32x16_bf16 v[32:47], v[8:11], v[0:3], v[32:47]
	v_lshlrev_b32_e32 v0, 2, v198
	s_movk_i32 s0, 0x84
	v_and_b32_e32 v52, 28, v0
	v_mul_lo_u32 v1, v65, s0
	v_lshl_add_u32 v2, v52, 2, v1
	s_barrier
	ds_read_b32 v0, v2 offset:36864
	v_cmp_eq_u32_e32 vcc, 0, v52
	v_cmp_ne_u32_e64 s[0:1], 0, v52
	s_waitcnt lgkmcnt(0)
	v_add_f32_e32 v0, 0, v0
	s_and_saveexec_b64 s[8:9], s[0:1]
	s_cbranch_execz .LBB0_432
	ds_read_b32 v3, v2 offset:53756
	s_waitcnt lgkmcnt(0)
	v_add_f32_e32 v0, v0, v3
